# v10 + shift/mask tile scheduler + peeled first K-iteration (vmcnt(24)) + QK^T MFMAs as accumulator pairs + attention row-max/row-sum VALU trims
# speedup vs baseline: 1.0000x; 1.0000x over previous
.LBB0_1309:
	s_waitcnt lgkmcnt(7)
	v_mfma_f32_32x32x16_bf16 v[114:129], v[190:193], v[150:153], v[218:233]
	v_add_f32_e32 v98, v82, v83
	v_add_f32_e32 v98, v84, v98
	v_add_f32_e32 v98, v85, v98
	v_add_f32_e32 v98, v86, v98
	v_add_u32_e32 v247, s30, v246
	v_add_f32_e32 v98, v87, v98
	v_cvt_pk_bf16_f32 v158, v82, v83
	v_cvt_pk_bf16_f32 v159, v84, v85
	s_nop 0
	v_add_f32_e32 v82, v88, v98
	s_waitcnt lgkmcnt(6)
	v_mfma_f32_32x32x16_bf16 v[114:129], v[186:189], v[146:149], v[114:129]
	v_add_f32_e32 v82, v89, v82
	v_add_f32_e32 v82, v90, v82
	v_add_f32_e32 v82, v91, v82
	v_cvt_pk_bf16_f32 v160, v86, v87
	v_cvt_pk_bf16_f32 v161, v88, v89
	s_waitcnt lgkmcnt(5)
	v_mfma_f32_32x32x16_bf16 v[98:113], v[182:185], v[150:153], v[218:233]
	v_add_f32_e32 v82, v92, v82
	v_add_f32_e32 v82, v93, v82
	v_add_f32_e32 v82, v94, v82
	v_add_f32_e32 v82, v95, v82
	v_cvt_pk_bf16_f32 v154, v90, v91
	v_cvt_pk_bf16_f32 v155, v92, v93
	s_waitcnt lgkmcnt(4)
	v_mfma_f32_32x32x16_bf16 v[98:113], v[178:181], v[146:149], v[98:113]
	v_add_f32_e32 v82, v96, v82
	v_add_f32_e32 v82, v97, v82
	v_add_f32_e32 v82, v66, v82
	v_add_f32_e32 v86, v67, v82
	v_cvt_pk_bf16_f32 v156, v94, v95
	v_cvt_pk_bf16_f32 v157, v96, v97
	ds_read_b64_tr_b16 v[82:83], v247 offset:49152
	ds_read_b64_tr_b16 v[84:85], v247 offset:49664
	s_waitcnt lgkmcnt(5)
	v_mfma_f32_32x32x16_bf16 v[114:129], v[174:177], v[142:145], v[114:129]
	v_add_f32_e32 v86, v68, v86
	v_add_f32_e32 v86, v69, v86
	v_add_f32_e32 v86, v70, v86
	v_add_f32_e32 v86, v71, v86
	v_cvt_pk_bf16_f32 v138, v66, v67
	v_cvt_pk_bf16_f32 v139, v68, v69
	ds_read_b64_tr_b16 v[66:67], v247 offset:50176
	ds_read_b64_tr_b16 v[68:69], v247 offset:50688
	v_lshl_add_u64 v[188:189], v[214:215], 0, s[52:53]
	v_lshl_add_u64 v[92:93], v[188:189], 0, s[70:71]
	s_add_i32 s27, s91, s25
	s_mov_b32 s30, m0
	s_mov_b32 m0, s27
	s_nop 0
	global_load_lds_dwordx4 v[92:93], off
	s_mov_b32 m0, s30
	s_waitcnt lgkmcnt(6)
	v_mfma_f32_32x32x16_bf16 v[114:129], v[166:169], v[134:137], v[114:129]
	v_add_f32_e32 v86, v72, v86
	v_add_f32_e32 v86, v73, v86
	v_add_f32_e32 v86, v74, v86
	v_add_f32_e32 v86, v75, v86
	v_cvt_pk_bf16_f32 v140, v70, v71
	v_cvt_pk_bf16_f32 v141, v72, v73
	ds_read_b64_tr_b16 v[70:71], v247 offset:53248
	ds_read_b64_tr_b16 v[72:73], v247 offset:53760
	v_lshl_add_u64 v[92:93], v[188:189], 0, s[72:73]
	v_lshl_add_u64 v[186:187], v[216:217], 0, s[52:53]
	s_addk_i32 s27, 0x2000
	s_mov_b32 s30, m0
	s_mov_b32 m0, s27
	s_nop 0
	global_load_lds_dwordx4 v[92:93], off
	s_mov_b32 m0, s30
	s_waitcnt lgkmcnt(7)
	v_mfma_f32_32x32x16_bf16 v[98:113], v[170:173], v[142:145], v[98:113]
	v_add_f32_e32 v86, v76, v86
	v_add_f32_e32 v86, v77, v86
	v_add_f32_e32 v86, v78, v86
	v_add_f32_e32 v86, v79, v86
	v_cvt_pk_bf16_f32 v130, v74, v75
	v_cvt_pk_bf16_f32 v131, v76, v77
	ds_read_b64_tr_b16 v[74:75], v247 offset:54272
	ds_read_b64_tr_b16 v[76:77], v247 offset:54784
	v_lshl_add_u64 v[92:93], v[186:187], 0, s[74:75]
	s_add_i32 s27, s29, s24
	s_mov_b32 s30, m0
	s_mov_b32 m0, s27
	s_nop 0
	global_load_lds_dwordx4 v[92:93], off
	s_mov_b32 m0, s30
	s_waitcnt lgkmcnt(8)
	v_mfma_f32_32x32x16_bf16 v[98:113], v[162:165], v[134:137], v[98:113]
	v_add_f32_e32 v86, v80, v86
	v_add_f32_e32 v86, v81, v86
	v_cvt_pk_bf16_f32 v132, v78, v79
	v_cvt_pk_bf16_f32 v133, v80, v81
	v_lshl_add_u64 v[92:93], v[186:187], 0, s[76:77]
	s_addk_i32 s27, 0x2000
	s_mov_b32 s30, m0
	s_mov_b32 m0, s27
	s_nop 0
	global_load_lds_dwordx4 v[92:93], off
	s_mov_b32 m0, s30
	s_waitcnt lgkmcnt(6)
	v_mfma_f32_32x32x16_bf16 v[18:33], v[158:161], v[82:85], v[18:33]
	ds_read_b64_tr_b16 v[78:79], v247 offset:57344
	ds_read_b64_tr_b16 v[80:81], v247 offset:57856
	v_max_f32_e32 v94, v114, v115
	v_max3_f32 v95, v116, v117, v99
	v_max3_f32 v94, v94, v98, v100
	v_max3_f32 v94, v94, v101, v118
	v_max3_f32 v95, v95, v120, v121
	v_max3_f32 v94, v94, v119, v102
	v_max3_f32 v95, v95, v104, v105
	s_waitcnt lgkmcnt(6)
	v_mfma_f32_32x32x16_bf16 v[18:33], v[154:157], v[66:69], v[18:33]
	ds_read_b64_tr_b16 v[66:67], v247 offset:58368
	ds_read_b64_tr_b16 v[68:69], v247 offset:58880
	v_max3_f32 v94, v94, v103, v122
	v_max3_f32 v95, v95, v124, v125
	v_max3_f32 v94, v94, v123, v106
	v_max3_f32 v95, v95, v108, v109
	v_max3_f32 v94, v94, v107, v126
	v_max3_f32 v95, v95, v128, v129
	v_max3_f32 v94, v94, v127, v110
	v_max3_f32 v95, v95, v112, v113
	v_max3_f32 v94, v94, v111, v95
	s_waitcnt lgkmcnt(6)
	v_mfma_f32_32x32x16_bf16 v[50:65], v[158:161], v[70:73], v[50:65]
	ds_read_b64_tr_b16 v[70:71], v247 offset:61440
	ds_read_b64_tr_b16 v[72:73], v247 offset:61952
	v_mov_b32_e32 v95, v94
	s_nop 1
	v_permlane32_swap_b32_e32 v94, v95
	v_max_f32_e32 v94, v94, v95
	v_cmp_lt_f32_e32 vcc, s93, v94
	s_cmp_lg_u64 vcc, 0
	v_add_f32_e32 v190, v250, v86
	s_cselect_b64 s[36:37], -1, 0
	s_cbranch_vccnz .LBB0_1317

.LBB0_1312:
	s_add_i32 s27, s29, 0x4000
	s_cmpk_lg_u32 s29, 0x8000
	s_cselect_b32 s27, s27, 0
	v_mfma_f32_32x32x16_bf16 v[82:97], v[70:73], v[150:153], v[218:233]
	v_add_f32_e32 v74, v114, v115
	v_add_f32_e32 v74, v116, v74
	v_add_f32_e32 v74, v117, v74
	v_add_f32_e32 v74, v118, v74
	v_add_u32_e32 v247, s91, v246
	v_add_f32_e32 v74, v119, v74
	v_cvt_pk_bf16_f32 v158, v114, v115
	v_cvt_pk_bf16_f32 v159, v116, v117
	s_nop 0
	v_add_f32_e32 v70, v120, v74
	v_add_f32_e32 v70, v121, v70
	v_add_f32_e32 v70, v122, v70
	v_add_f32_e32 v114, v123, v70
	v_mfma_f32_32x32x16_bf16 v[82:97], v[182:185], v[146:149], v[82:97]
	v_cvt_pk_bf16_f32 v160, v118, v119
	v_cvt_pk_bf16_f32 v161, v120, v121
	v_mfma_f32_32x32x16_bf16 v[66:81], v[66:69], v[150:153], v[218:233]
	v_add_f32_e32 v114, v124, v114
	v_add_f32_e32 v114, v125, v114
	v_add_f32_e32 v114, v126, v114
	v_add_f32_e32 v114, v127, v114
	v_cvt_pk_bf16_f32 v154, v122, v123
	v_cvt_pk_bf16_f32 v155, v124, v125
	v_mfma_f32_32x32x16_bf16 v[66:81], v[174:177], v[146:149], v[66:81]
	v_add_f32_e32 v114, v128, v114
	v_add_f32_e32 v114, v129, v114
	v_add_f32_e32 v114, v98, v114
	v_add_f32_e32 v118, v99, v114
	v_cvt_pk_bf16_f32 v156, v126, v127
	v_cvt_pk_bf16_f32 v157, v128, v129
	ds_read_b64_tr_b16 v[114:115], v247 offset:49152
	ds_read_b64_tr_b16 v[116:117], v247 offset:49664
	v_mfma_f32_32x32x16_bf16 v[82:97], v[178:181], v[142:145], v[82:97]
	v_add_f32_e32 v118, v100, v118
	v_add_f32_e32 v118, v101, v118
	v_add_f32_e32 v118, v102, v118
	v_add_f32_e32 v118, v103, v118
	v_cvt_pk_bf16_f32 v138, v98, v99
	v_cvt_pk_bf16_f32 v139, v100, v101
	ds_read_b64_tr_b16 v[98:99], v247 offset:50176
	ds_read_b64_tr_b16 v[100:101], v247 offset:50688
	s_mov_b64 s[30:31], 0x1dd40000
	v_lshl_add_u64 v[124:125], v[188:189], 0, s[30:31]
	s_add_i32 s36, s29, s25
	s_mov_b32 s30, m0
	s_mov_b32 m0, s36
	s_nop 0
	global_load_lds_dwordx4 v[124:125], off
	s_mov_b32 m0, s30
	v_mfma_f32_32x32x16_bf16 v[82:97], v[170:173], v[134:137], v[82:97]
	v_add_f32_e32 v118, v104, v118
	v_add_f32_e32 v118, v105, v118
	v_add_f32_e32 v118, v106, v118
	v_add_f32_e32 v118, v107, v118
	v_cvt_pk_bf16_f32 v140, v102, v103
	v_cvt_pk_bf16_f32 v141, v104, v105
	ds_read_b64_tr_b16 v[102:103], v247 offset:53248
	ds_read_b64_tr_b16 v[104:105], v247 offset:53760
	s_mov_b64 s[30:31], 0x1dd40080
	v_lshl_add_u64 v[124:125], v[188:189], 0, s[30:31]
	s_add_i32 s30, s36, 0x2000
	s_mov_b32 s31, m0
	s_mov_b32 m0, s30
	s_nop 0
	global_load_lds_dwordx4 v[124:125], off
	s_mov_b32 m0, s31
	v_mfma_f32_32x32x16_bf16 v[66:81], v[166:169], v[142:145], v[66:81]
	v_add_f32_e32 v118, v108, v118
	v_add_f32_e32 v118, v109, v118
	v_add_f32_e32 v118, v110, v118
	v_add_f32_e32 v118, v111, v118
	v_cvt_pk_bf16_f32 v130, v106, v107
	v_cvt_pk_bf16_f32 v131, v108, v109
	ds_read_b64_tr_b16 v[106:107], v247 offset:54272
	ds_read_b64_tr_b16 v[108:109], v247 offset:54784
	s_mov_b64 s[30:31], 0x25cc0000
	v_lshl_add_u64 v[124:125], v[186:187], 0, s[30:31]
	s_add_i32 s36, s27, s24
	s_mov_b32 s30, m0
	s_mov_b32 m0, s36
	s_nop 0
	global_load_lds_dwordx4 v[124:125], off
	s_mov_b32 m0, s30
	v_mfma_f32_32x32x16_bf16 v[66:81], v[162:165], v[134:137], v[66:81]
	v_add_f32_e32 v118, v112, v118
	v_add_f32_e32 v118, v113, v118
	v_cvt_pk_bf16_f32 v132, v110, v111
	v_cvt_pk_bf16_f32 v133, v112, v113
	s_mov_b64 s[30:31], 0x25cc0080
	v_lshl_add_u64 v[124:125], v[186:187], 0, s[30:31]
	s_add_i32 s30, s36, 0x2000
	s_mov_b32 s31, m0
	s_mov_b32 m0, s30
	s_nop 0
	global_load_lds_dwordx4 v[124:125], off
	s_mov_b32 m0, s31
	s_waitcnt lgkmcnt(6)
	v_mfma_f32_32x32x16_bf16 v[18:33], v[158:161], v[114:117], v[18:33]
	ds_read_b64_tr_b16 v[110:111], v247 offset:57344
	ds_read_b64_tr_b16 v[112:113], v247 offset:57856
	v_max_f32_e32 v122, v82, v83
	v_max3_f32 v123, v84, v85, v67
	v_max3_f32 v122, v122, v66, v68
	v_max3_f32 v122, v122, v69, v86
	v_max3_f32 v123, v123, v88, v89
	v_max3_f32 v122, v122, v87, v70
	v_max3_f32 v123, v123, v72, v73
	s_waitcnt lgkmcnt(6)
	v_mfma_f32_32x32x16_bf16 v[18:33], v[154:157], v[98:101], v[18:33]
	ds_read_b64_tr_b16 v[98:99], v247 offset:58368
	ds_read_b64_tr_b16 v[100:101], v247 offset:58880
	v_max3_f32 v122, v122, v71, v90
	v_max3_f32 v123, v123, v92, v93
	v_max3_f32 v122, v122, v91, v74
	v_max3_f32 v123, v123, v76, v77
	v_max3_f32 v122, v122, v75, v94
	v_max3_f32 v123, v123, v96, v97
	v_max3_f32 v122, v122, v95, v78
	v_max3_f32 v123, v123, v80, v81
	v_max3_f32 v122, v122, v79, v123
	s_waitcnt lgkmcnt(6)
	v_mfma_f32_32x32x16_bf16 v[50:65], v[158:161], v[102:105], v[50:65]
	ds_read_b64_tr_b16 v[102:103], v247 offset:61440
	ds_read_b64_tr_b16 v[104:105], v247 offset:61952
	v_mov_b32_e32 v123, v122
	s_nop 1
	v_permlane32_swap_b32_e32 v122, v123
	v_max_f32_e32 v122, v122, v123
	v_cmp_lt_f32_e32 vcc, s93, v122
	s_cmp_lg_u64 vcc, 0
	v_add_f32_e32 v250, v190, v118
	s_cselect_b64 s[36:37], -1, 0
	s_cbranch_vccnz .LBB0_1320
